# workgroups 192..255 (longest path): the arrival-counter check + acquire before their deferred conv fix-up is done early by idle wave 7 during quarter-unit K/V staging (LDS flag), skipped afterwards
# speedup vs baseline: 1.0058x; 1.0058x over previous
; #define LAS __attribute__((address_space(3)))
; __device__ __forceinline__ unsigned xb_ld(unsigned* p)              { return __hip_atomic_load(p, __ATOMIC_RELAXED, __HIP_MEMORY_SCOPE_AGENT); }
; __device__ __forceinline__ void attn_unit(LAS unsigned char* lds, int unit, int mode, const bf16* QKVG, const float* sinks, const float* gain_a, bf16* MIX, float* SSA) {
;     ...
;     __syncthreads();
;     constexpr float LOG2E = 1.4426950408889634f;
;     const float slope2 = exp2f(-0.5f * (float)(h + 1)) * LOG2E, sink2 = sinks[h] * LOG2E;
;     LAS float* GN = SS + 8 * 128 + w * 64;
;     GN[lane] = gain_a[h * 64 + lane];
; #pragma unroll
;     for (int k = 0; k < 4; ++k) *(LAS v4u*)(wt_row + 8 * k * KP) = qrow[k];
; #pragma unroll
;     for (int s = 0; s < 4; ++s) qr[s] = *(const LAS bf16x8*)(wt_frq + 16 * s);
;     for (int i = i0; i < i1; ++i) {
;         const int inx = (i < 3) ? (i + 1) : 3;
; #pragma unroll
;         for (int k = 0; k < 4; ++k) qrow[k] = __builtin_nontemporal_load((const v4u*)(qrow0 + (size_t)(32 * inx + 8 * k) * QP));
; #pragma unroll
;         for (int k = 0; k < 4; ++k) grow[k] = __builtin_nontemporal_load((const v4u*)(grow0 + (size_t)(32 * i + 8 * k) * QP));
;         int qq = q - 4 * hh; asm volatile("" : "+v"(qq));
;         float base = slope2 * (float)(4 * hh); asm volatile("" : "+v"(base));
;         f32x16 st[5];
; #pragma unroll
;         for (int j = 0; j < 5; ++j) {
;             const bool tile_ok = !(nblk == 0 && (i + j) < 4);
;             const float sl = tile_ok ? slope2 : 0.f, bs = tile_ok ? base : -INFINITY;
; #pragma unroll
;             for (int r = 0; r < 16; ++r) st[j][r] = fmaf(sl, (float)((r & 3) + 8 * (r >> 2) + 32 * j), bs);
; __device__ __forceinline__ void group_wait(unsigned* cnt, unsigned want, unsigned* bar) {
;     if (threadIdx.x == 0) {
;         unsigned sp = 0;
;         while (__hip_atomic_load(cnt, __ATOMIC_RELAXED, __HIP_MEMORY_SCOPE_AGENT) < want) {
;             __builtin_amdgcn_s_sleep(2);
;             if ((++sp & 255u) == 0u) { if (xb_ld(&bar[XB_TMO])) break; if (sp > XB_SPIN_CAP) { atomicAdd(&bar[XB_TMO], 1u); break; } }
;         }
;         __builtin_amdgcn_fence(__ATOMIC_ACQUIRE, "agent");
;         asm volatile("s_waitcnt vmcnt(0)" ::: "memory");
;     }
;     __syncthreads();
.LBB0_309:
	s_or_b64 exec, exec, s[0:1]
	s_cmp_lt_u32 s98, 192
	s_cbranch_scc1 .Lea_skip
	v_readlane_b32 s0, v253, 29
	s_nop 2
	s_cmp_lg_u32 s0, 7
	s_cbranch_scc1 .Lea_skip
	v_mov_b32_e32 v234, 0
	global_load_dword v235, v234, s[8:9] sc1
	s_waitcnt vmcnt(0)
	v_readfirstlane_b32 s0, v235
	s_nop 3
	s_cmp_lt_u32 s0, 32
	s_cbranch_scc1 .Lea_skip
	buffer_inv sc1
	s_waitcnt vmcnt(0)
	v_mov_b32_e32 v234, 0x20448
	v_mov_b32_e32 v235, 1
	ds_write_b32 v234, v235
	s_waitcnt lgkmcnt(0)
.Lea_skip:
	v_readlane_b32 s36, v253, 4
	v_readlane_b32 s44, v253, 12
	v_readlane_b32 s45, v253, 13
	v_readlane_b32 s46, v253, 14
	v_readlane_b32 s47, v253, 15
	v_readlane_b32 s48, v253, 16
	v_readlane_b32 s49, v253, 17
	s_mov_b64 s[24:25], s[44:45]
	v_or_b32_e32 v132, s14, v231
	v_mov_b32_e32 v133, 0
	s_mov_b64 s[28:29], s[48:49]
	v_lshl_add_u64 v[16:17], v[132:133], 2, s[28:29]
	s_waitcnt lgkmcnt(0)
	s_barrier
	s_add_i32 s4, s7, 1
	v_cvt_f32_u32_e32 v20, s4
	s_mul_i32 s0, s13, 0x1200
	s_add_i32 s0, s0, 0
	v_lshlrev_b32_e32 v16, 1, v130
	s_add_i32 s0, s0, 0x12c00
	s_mov_b32 s5, 0xc2fc0000
	v_add3_u32 v137, s0, v123, v16
	v_mul_f32_e32 v16, -0.5, v20
	v_cmp_gt_f32_e32 vcc, s5, v16
	v_mov_b32_e32 v18, 0x42800000
	s_and_b64 s[4:5], vcc, exec
	v_lshlrev_b32_e32 v17, 1, v129
	v_add_u32_e32 v139, s0, v125
	v_cndmask_b32_e32 v16, 0, v18, vcc
	s_cselect_b32 s0, 0xffffffc0, 0
	s_lshl_b32 s4, s7, 2
	s_and_b32 s5, s6, 0x3fffffc0
	v_add_u32_e32 v138, 0, v17
	v_add_u32_e32 v25, v139, v17
	v_fmac_f32_e32 v16, -0.5, v20
	v_mov_b32_e32 v17, s4
	s_lshl_b32 s4, s5, 2
	v_exp_f32_e32 v16, v16
	s_add_i32 s16, s4, 0
	s_add_i32 s16, s16, 0x12400
	s_cmp_lg_u32 s18, 0
	s_cselect_b64 vcc, -1, 0
	s_add_i32 s17, s12, 1
	v_ldexp_f32 v16, v16, s0
	s_lshl_b32 s0, s17, 5
	s_cmp_eq_u32 s12, 3
	s_cselect_b64 s[6:7], -1, 0
	s_and_b64 s[4:5], s[6:7], exec
	v_cvt_f32_u32_e32 v19, v135
	s_cselect_b32 s0, 0x60, s0
	s_mov_b32 s1, 0
	s_mulk_i32 s0, 0x1200
	s_mov_b32 s19, 0x9000
	v_mul_f32_e32 v132, 0x3fb8aa3b, v16
	v_lshl_add_u64 v[16:17], v[50:51], 0, s[0:1]
	v_add_co_u32_e64 v18, s[4:5], s19, v16
	s_mov_b32 s20, 0x12000
	v_mul_f32_e32 v64, v132, v19
	v_addc_co_u32_e64 v19, s[4:5], 0, v17, s[4:5]
	v_add_co_u32_e64 v20, s[4:5], s20, v16
	s_mov_b32 s21, 0x1b000
	s_nop 0
	v_addc_co_u32_e64 v21, s[4:5], 0, v17, s[4:5]
	v_add_co_u32_e64 v22, s[4:5], s21, v16
	v_lshl_add_u32 v26, v231, 2, s16
	s_nop 0
	v_addc_co_u32_e64 v23, s[4:5], 0, v17, s[4:5]
	global_load_dwordx4 v[98:101], v[48:49], off offset:2560 nt
	global_load_dwordx4 v[82:85], v[16:17], off nt
	global_load_dwordx4 v[86:89], v[18:19], off nt
	global_load_dwordx4 v[90:93], v[20:21], off nt
	global_load_dwordx4 v[94:97], v[22:23], off nt
	v_sub_u32_e32 v140, v134, v135
	v_mov_b32_e32 v146, 0xff800000
	s_lshl_b32 s15, s12, 5
	s_mov_b32 s2, 0x42800000
	s_mov_b32 s3, 0x42820000
	v_readlane_b32 s37, v253, 5
	v_readlane_b32 s38, v253, 6
	v_readlane_b32 s39, v253, 7
	v_readlane_b32 s40, v253, 8
	s_waitcnt vmcnt(5)
	ds_write_b32 v26, v232
	ds_write_b128 v137, v[0:3]
	ds_write_b128 v137, v[4:7] offset:1152
	ds_write_b128 v137, v[8:11] offset:2304
	ds_write_b128 v137, v[12:15] offset:3456
	v_add_co_u32_e64 v0, s[4:5], s19, v48
	ds_read_b128 v[114:117], v25 offset:96
	ds_read_b128 v[118:121], v25 offset:64
	ds_read_b128 v[126:129], v25
	ds_read_b128 v[122:125], v25 offset:32
	v_addc_co_u32_e64 v1, s[4:5], 0, v49, s[4:5]
	v_add_co_u32_e64 v2, s[4:5], s20, v48
	v_readlane_b32 s41, v253, 9
	s_nop 0
	v_addc_co_u32_e64 v3, s[4:5], 0, v49, s[4:5]
	global_load_dwordx4 v[102:105], v[0:1], off offset:2560 nt
	global_load_dwordx4 v[106:109], v[2:3], off offset:2560 nt
	v_add_co_u32_e64 v0, s[4:5], s21, v48
	v_readlane_b32 s42, v253, 10
	s_nop 0
	v_addc_co_u32_e64 v1, s[4:5], 0, v49, s[4:5]
	s_mov_b32 s4, 2.0
	global_load_dwordx4 v[110:113], v[0:1], off offset:2560 nt
	v_cndmask_b32_e32 v0, 0, v132, vcc
	v_cndmask_b32_e32 v2, v146, v64, vcc
	s_mov_b32 s5, 0x40400000
	v_pk_fma_f32 v[50:51], v[0:1], s[4:5], v[2:3] op_sel_hi:[0,1,0]
	s_mov_b32 s4, 0x41000000
	s_mov_b32 s5, 0x41100000
	v_pk_fma_f32 v[52:53], v[0:1], s[4:5], v[2:3] op_sel_hi:[0,1,0]
	s_mov_b32 s4, 0x41200000
	s_mov_b32 s5, 0x41300000
	v_pk_fma_f32 v[54:55], v[0:1], s[4:5], v[2:3] op_sel_hi:[0,1,0]
	s_mov_b32 s4, 0x41800000
	s_mov_b32 s5, 0x41880000
	v_pk_fma_f32 v[56:57], v[0:1], s[4:5], v[2:3] op_sel_hi:[0,1,0]
	s_mov_b32 s4, 0x41900000
	s_mov_b32 s5, 0x41980000
	v_pk_fma_f32 v[58:59], v[0:1], s[4:5], v[2:3] op_sel_hi:[0,1,0]
	s_mov_b32 s4, 0x41c00000
	s_mov_b32 s5, 0x41c80000
	v_pk_fma_f32 v[60:61], v[0:1], s[4:5], v[2:3] op_sel_hi:[0,1,0]
	s_mov_b32 s4, 0x41d00000
	s_mov_b32 s5, 0x41d80000
	v_pk_fma_f32 v[62:63], v[0:1], s[4:5], v[2:3] op_sel_hi:[0,1,0]
	s_or_b64 s[4:5], vcc, s[6:7]
	v_fma_f32 v48, 0, v0, v2
	v_add_f32_e32 v49, v0, v2
	v_cndmask_b32_e64 v0, 0, v132, s[4:5]
	v_cndmask_b32_e64 v2, v146, v64, s[4:5]
	s_mov_b32 s4, 0x42680000
	s_mov_b32 s5, 0x426c0000
	v_pk_fma_f32 v[46:47], v[0:1], s[4:5], v[2:3] op_sel_hi:[0,1,0]
	s_mov_b32 s4, 0x42600000
	s_mov_b32 s5, 0x42640000
	v_pk_fma_f32 v[44:45], v[0:1], s[4:5], v[2:3] op_sel_hi:[0,1,0]
	s_mov_b32 s4, 0x42480000
	s_mov_b32 s5, 0x424c0000
	v_pk_fma_f32 v[42:43], v[0:1], s[4:5], v[2:3] op_sel_hi:[0,1,0]
	s_mov_b32 s4, 0x42400000
	s_mov_b32 s5, 0x42440000
	v_pk_fma_f32 v[40:41], v[0:1], s[4:5], v[2:3] op_sel_hi:[0,1,0]
	s_mov_b32 s4, 0x42280000
	s_mov_b32 s5, 0x422c0000
	v_pk_fma_f32 v[38:39], v[0:1], s[4:5], v[2:3] op_sel_hi:[0,1,0]
	s_mov_b32 s4, 0x42200000
	s_mov_b32 s5, 0x42240000
	v_pk_fma_f32 v[36:37], v[0:1], s[4:5], v[2:3] op_sel_hi:[0,1,0]
	s_mov_b32 s4, 0x42080000
	s_mov_b32 s5, 0x420c0000
	v_pk_fma_f32 v[34:35], v[0:1], s[4:5], v[2:3] op_sel_hi:[0,1,0]
; #define LAS __attribute__((address_space(3)))
; __device__ __forceinline__ void attn_unit(LAS unsigned char* lds, int unit, int mode, const bf16* QKVG, const float* sinks, const float* gain_a, bf16* MIX, float* SSA) {
;     ...
;         f32x16 st[5];
; #pragma unroll
;         for (int j = 0; j < 5; ++j) {
;             const bool tile_ok = !(nblk == 0 && (i + j) < 4);
;             const float sl = tile_ok ? slope2 : 0.f, bs = tile_ok ? base : -INFINITY;
; #pragma unroll
;             for (int r = 0; r < 16; ++r) st[j][r] = fmaf(sl, (float)((r & 3) + 8 * (r >> 2) + 32 * j), bs);
;         }
;         {
;             const LAS bf16* kp = Ks + (32 * i + q) * KP + hh * 8;
;             bf16x8 kf[2][5];
; #pragma unroll
;             for (int j = 0; j < 5; ++j) kf[0][j] = *(const LAS bf16x8*)(kp + j * 32 * KP);
; #pragma unroll
;             for (int s = 0; s < 4; ++s) {
;                 if (s < 3) {
; #pragma unroll
;                     for (int j = 0; j < 5; ++j) kf[(s + 1) & 1][j] = *(const LAS bf16x8*)(kp + j * 32 * KP + 16 * (s + 1));
;                 }
; #pragma unroll
;                 for (int j = 0; j < 5; ++j) st[j] = __builtin_amdgcn_mfma_f32_32x32x16_bf16(kf[s & 1][j], qr[s], st[j], 0, 0, 0);
;             }
;         }
	s_mov_b32 s4, 0x42000000
	s_mov_b32 s5, 0x42040000
	s_cmp_gt_u32 s12, 1
	v_pk_fma_f32 v[32:33], v[0:1], s[4:5], v[2:3] op_sel_hi:[0,1,0]
	s_cselect_b64 s[4:5], -1, 0
	s_or_b64 vcc, vcc, s[4:5]
	s_mov_b32 s4, 0x42b40000
	v_cndmask_b32_e32 v0, 0, v132, vcc
	v_cndmask_b32_e32 v2, v146, v64, vcc
	s_mov_b32 s5, 0x42b60000
	v_pk_fma_f32 v[30:31], v[0:1], s[4:5], v[2:3] op_sel_hi:[0,1,0]
	s_mov_b32 s4, 0x42b00000
	s_mov_b32 s5, 0x42b20000
	v_pk_fma_f32 v[28:29], v[0:1], s[4:5], v[2:3] op_sel_hi:[0,1,0]
	s_mov_b32 s4, 0x42a40000
	s_mov_b32 s5, 0x42a60000
	v_pk_fma_f32 v[26:27], v[0:1], s[4:5], v[2:3] op_sel_hi:[0,1,0]
	s_mov_b32 s4, 0x42a00000
	s_mov_b32 s5, 0x42a20000
	v_pk_fma_f32 v[24:25], v[0:1], s[4:5], v[2:3] op_sel_hi:[0,1,0]
	s_mov_b32 s4, 0x42940000
	s_mov_b32 s5, 0x42960000
	v_pk_fma_f32 v[22:23], v[0:1], s[4:5], v[2:3] op_sel_hi:[0,1,0]
	s_mov_b32 s4, 0x42900000
	s_mov_b32 s5, 0x42920000
	s_or_b32 s0, s12, s18
	v_pk_fma_f32 v[20:21], v[0:1], s[4:5], v[2:3] op_sel_hi:[0,1,0]
	s_mov_b32 s4, 0x42840000
	s_cmp_eq_u32 s0, 0
	s_mov_b32 s5, 0x42860000
	v_pk_fma_f32 v[16:17], v[0:1], s[2:3], v[2:3] op_sel_hi:[0,1,0]
	s_cselect_b64 vcc, -1, 0
	s_mov_b32 s2, 0x42f40000
	v_pk_fma_f32 v[18:19], v[0:1], s[4:5], v[2:3] op_sel_hi:[0,1,0]
	v_cndmask_b32_e64 v0, v132, 0, vcc
	v_cndmask_b32_e32 v70, v64, v146, vcc
	s_mov_b32 s3, 0x42f60000
	v_pk_fma_f32 v[14:15], v[0:1], s[2:3], v[70:71] op_sel_hi:[0,1,0]
	s_mov_b32 s2, 0x42f00000
	s_mov_b32 s3, 0x42f20000
	v_pk_fma_f32 v[12:13], v[0:1], s[2:3], v[70:71] op_sel_hi:[0,1,0]
	s_mov_b32 s2, 0x42e40000
	s_mov_b32 s3, 0x42e60000
	v_pk_fma_f32 v[10:11], v[0:1], s[2:3], v[70:71] op_sel_hi:[0,1,0]
	s_mov_b32 s2, 0x42e00000
	s_mov_b32 s3, 0x42e20000
	v_pk_fma_f32 v[8:9], v[0:1], s[2:3], v[70:71] op_sel_hi:[0,1,0]
	s_mov_b32 s2, 0x42d40000
	s_mov_b32 s3, 0x42d60000
	v_pk_fma_f32 v[6:7], v[0:1], s[2:3], v[70:71] op_sel_hi:[0,1,0]
	s_mov_b32 s2, 0x42d00000
	s_mov_b32 s3, 0x42d20000
	v_pk_fma_f32 v[4:5], v[0:1], s[2:3], v[70:71] op_sel_hi:[0,1,0]
	s_mov_b32 s2, 0x42c40000
	s_mov_b32 s3, 0x42c60000
	v_pk_fma_f32 v[2:3], v[0:1], s[2:3], v[70:71] op_sel_hi:[0,1,0]
	v_or_b32_e32 v1, s15, v134
	s_movk_i32 s0, 0x90
	v_mad_u32_u24 v147, v1, s0, v138
	s_mov_b32 s2, 0x42c00000
	ds_read_b128 v[66:69], v147
	s_mov_b32 s3, 0x42c20000
	v_pk_fma_f32 v[0:1], v[0:1], s[2:3], v[70:71] op_sel_hi:[0,1,0]
	s_mov_b32 s2, 0x431a0000
	s_mov_b32 s3, 0x431b0000
	v_pk_fma_f32 v[78:79], v[132:133], s[2:3], v[64:65] op_sel_hi:[0,1,0]
	s_mov_b32 s2, 0x43180000
	s_mov_b32 s3, 0x43190000
	ds_read_b128 v[70:73], v147 offset:4608
	ds_read_b128 v[142:145], v147 offset:32
	v_pk_fma_f32 v[76:77], v[132:133], s[2:3], v[64:65] op_sel_hi:[0,1,0]
	s_mov_b32 s2, 0x43120000
	s_mov_b32 s3, 0x43130000
	v_pk_fma_f32 v[74:75], v[132:133], s[2:3], v[64:65] op_sel_hi:[0,1,0]
	s_mov_b32 s2, 0x43100000
	s_mov_b32 s3, 0x43110000
	s_waitcnt lgkmcnt(2)
	v_mfma_f32_32x32x16_bf16 v[48:63], v[66:69], v[126:129], v[48:63]
	ds_read_b128 v[66:69], v147 offset:9216
	ds_read_b128 v[150:153], v147 offset:4640
	ds_read_b128 v[154:157], v147 offset:13824
	ds_read_b128 v[172:175], v147 offset:9248
	ds_read_b128 v[176:179], v147 offset:18432
	ds_read_b128 v[180:183], v147 offset:13856
	v_cmp_gt_i32_e32 vcc, 0, v140
	s_lshl_b32 s0, s12, 6
	v_readlane_b32 s43, v253, 11
	v_readlane_b32 s50, v253, 18
	s_waitcnt lgkmcnt(7)
	v_mfma_f32_32x32x16_bf16 v[32:47], v[70:73], v[126:129], v[32:47]
	v_fma_f32 v72, v132, s2, v64
	v_fma_f32 v73, v132, s3, v64
	s_mov_b32 s2, 0x430a0000
	s_mov_b32 s3, 0x430b0000
	v_fma_f32 v70, v132, s2, v64
	v_fma_f32 v71, v132, s3, v64
	s_mov_b32 s2, 0x43080000
	s_mov_b32 s3, 0x43090000
	v_readlane_b32 s51, v253, 19
	s_waitcnt lgkmcnt(5)
	v_mfma_f32_32x32x16_bf16 v[16:31], v[66:69], v[126:129], v[16:31]
	v_fma_f32 v68, v132, s2, v64
	v_fma_f32 v69, v132, s3, v64
	s_mov_b32 s2, 0x43020000
	s_mov_b32 s3, 0x43030000
	v_fma_f32 v66, v132, s2, v64
	v_fma_f32 v67, v132, s3, v64
	s_mov_b32 s2, 0x43000000
	s_mov_b32 s3, 0x43010000
	v_pk_fma_f32 v[64:65], v[132:133], s[2:3], v[64:65] op_sel_hi:[0,1,0]
	s_waitcnt lgkmcnt(3)
	v_mfma_f32_32x32x16_bf16 v[0:15], v[154:157], v[126:129], v[0:15]
	ds_read_b128 v[154:157], v147 offset:18464
	s_movk_i32 s2, 0x80
	s_mov_b64 s[26:27], s[46:47]
	s_waitcnt lgkmcnt(2)
	v_mfma_f32_32x32x16_bf16 v[64:79], v[176:179], v[126:129], v[64:79]
	v_mfma_f32_32x32x16_bf16 v[48:63], v[142:145], v[122:125], v[48:63]
	v_mfma_f32_32x32x16_bf16 v[32:47], v[150:153], v[122:125], v[32:47]
	v_mfma_f32_32x32x16_bf16 v[16:31], v[172:175], v[122:125], v[16:31]
	s_waitcnt lgkmcnt(1)
	v_mfma_f32_32x32x16_bf16 v[0:15], v[180:183], v[122:125], v[0:15]
	s_waitcnt lgkmcnt(0)
	v_mfma_f32_32x32x16_bf16 v[64:79], v[154:157], v[122:125], v[64:79]
	ds_read_b128 v[122:125], v147 offset:64
	ds_read_b128 v[126:129], v147 offset:96
	s_waitcnt lgkmcnt(1)
	v_mfma_f32_32x32x16_bf16 v[48:63], v[122:125], v[118:121], v[48:63]
	ds_read_b128 v[122:125], v147 offset:4672
	ds_read_b128 v[142:145], v147 offset:4704
	s_waitcnt lgkmcnt(1)
	v_mfma_f32_32x32x16_bf16 v[32:47], v[122:125], v[118:121], v[32:47]
	ds_read_b128 v[122:125], v147 offset:9280
	ds_read_b128 v[150:153], v147 offset:9312
	s_waitcnt lgkmcnt(1)
	v_mfma_f32_32x32x16_bf16 v[16:31], v[122:125], v[118:121], v[16:31]
	ds_read_b128 v[122:125], v147 offset:13888
	ds_read_b128 v[154:157], v147 offset:13920
	s_waitcnt lgkmcnt(1)
	v_mfma_f32_32x32x16_bf16 v[0:15], v[122:125], v[118:121], v[0:15]
	ds_read_b128 v[122:125], v147 offset:18496
	ds_read_b128 v[172:175], v147 offset:18528
	s_waitcnt lgkmcnt(1)
	v_mfma_f32_32x32x16_bf16 v[64:79], v[122:125], v[118:121], v[64:79]
	v_or_b32_e32 v119, 0x80, v135
	v_cvt_f32_u32_e32 v119, v119
	v_cvt_f32_i32_e32 v120, v140
	s_waitcnt vmcnt(8)
; __device__ __forceinline__ void attn_unit(LAS unsigned char* lds, int unit, int mode, const bf16* QKVG, const float* sinks, const float* gain_a, bf16* MIX, float* SSA) {
;     ...
;         const float sinkq = fmaf(slope2, (float)(128 + 4 * hh) + (float)qq, sink2);
;         float mx = sinkq;
; #pragma unroll
;         for (int r = 0; r < 16; ++r) {
;             const int cr = (r & 3) + 8 * (r >> 2);
;             const bool up = cr > qq;
;             st[0][r] = up ? st[0][r] : -INFINITY;
;             st[4][r] = up ? -INFINITY : st[4][r];
;         }
; #pragma unroll
;         for (int j = 0; j < 5; ++j)
; #pragma unroll
;             for (int r = 0; r < 16; ++r) mx = fmaxf(mx, st[j][r]);
;         mx = fmaxf(mx, __shfl_xor(mx, 32));
;         float sum = 0.f;
; #pragma unroll
;         for (int j = 0; j < 5; ++j)
; #pragma unroll
;             for (int r = 0; r < 16; ++r) { const float p = __builtin_amdgcn_exp2f(st[j][r] - mx); st[j][r] = p; sum += p; }
	v_mul_f32_e32 v118, 0x3fb8aa3b, v141
	v_add_f32_e32 v120, v119, v120
	v_mfma_f32_32x32x16_bf16 v[48:63], v[126:129], v[114:117], v[48:63]
	v_fmac_f32_e32 v118, v132, v120
	s_waitcnt lgkmcnt(0)
	v_mfma_f32_32x32x16_bf16 v[64:79], v[172:175], v[114:117], v[64:79]
	s_nop 8
	v_cndmask_b32_e32 v121, v146, v48, vcc
	v_mfma_f32_32x32x16_bf16 v[32:47], v[142:145], v[114:117], v[32:47]
	s_nop 0
	v_cndmask_b32_e32 v119, v64, v146, vcc
	v_cmp_gt_i32_e32 vcc, 1, v140
	s_nop 1
	v_cndmask_b32_e32 v122, v146, v49, vcc
	v_max3_f32 v48, v118, v121, v122
	v_mfma_f32_32x32x16_bf16 v[16:31], v[150:153], v[114:117], v[16:31]
	v_mfma_f32_32x32x16_bf16 v[0:15], v[154:157], v[114:117], v[0:15]
	v_cndmask_b32_e32 v115, v65, v146, vcc
	v_cmp_gt_i32_e32 vcc, 2, v140
	s_nop 1
	v_cndmask_b32_e32 v123, v146, v50, vcc
	v_cndmask_b32_e32 v116, v66, v146, vcc
	v_cmp_gt_i32_e32 vcc, 3, v140
	s_nop 1
	v_cndmask_b32_e32 v124, v146, v51, vcc
	v_cndmask_b32_e32 v117, v67, v146, vcc
	v_cmp_gt_i32_e32 vcc, 8, v140
	v_max3_f32 v48, v48, v123, v124
	s_nop 0
	v_cndmask_b32_e32 v125, v146, v52, vcc
	v_cndmask_b32_e32 v114, v68, v146, vcc
	v_cmp_gt_i32_e32 vcc, 9, v140
	s_nop 1
	v_cndmask_b32_e32 v126, v146, v53, vcc
	v_cndmask_b32_e32 v68, v69, v146, vcc
	v_cmp_gt_i32_e32 vcc, 10, v140
	v_max3_f32 v48, v48, v125, v126
	s_nop 0
	v_cndmask_b32_e32 v69, v146, v54, vcc
	v_cndmask_b32_e32 v67, v70, v146, vcc
	v_cmp_gt_i32_e32 vcc, 11, v140
	s_nop 1
	v_cndmask_b32_e32 v70, v146, v55, vcc
	v_cndmask_b32_e32 v65, v71, v146, vcc
	v_cmp_gt_i32_e32 vcc, 16, v140
	v_max3_f32 v48, v48, v69, v70
	s_nop 0
	v_cndmask_b32_e32 v71, v146, v56, vcc
	v_cndmask_b32_e32 v66, v72, v146, vcc
	v_cmp_gt_i32_e32 vcc, 17, v140
	s_nop 1
	v_cndmask_b32_e32 v72, v146, v57, vcc
	v_cndmask_b32_e32 v64, v73, v146, vcc
	v_cmp_gt_i32_e32 vcc, 18, v140
	v_max3_f32 v48, v48, v71, v72
	s_nop 0
	v_cndmask_b32_e32 v73, v146, v58, vcc
	v_cndmask_b32_e32 v57, v74, v146, vcc
	v_cmp_gt_i32_e32 vcc, 19, v140
	s_nop 1
	v_cndmask_b32_e32 v59, v146, v59, vcc
	v_cndmask_b32_e32 v56, v75, v146, vcc
	v_cmp_gt_i32_e32 vcc, 24, v140
	v_max3_f32 v48, v48, v73, v59
	v_mul_u32_u24_e32 v75, 0x210, v134
	v_cndmask_b32_e32 v60, v146, v60, vcc
	v_cndmask_b32_e32 v53, v76, v146, vcc
	v_cmp_gt_i32_e32 vcc, 25, v140
	s_nop 1
	v_cndmask_b32_e32 v61, v146, v61, vcc
	v_cndmask_b32_e32 v54, v77, v146, vcc
	v_cmp_gt_i32_e32 vcc, 26, v140
	v_max3_f32 v48, v48, v60, v61
	s_nop 0
	v_cndmask_b32_e32 v62, v146, v62, vcc
	v_cndmask_b32_e32 v55, v78, v146, vcc
	v_cmp_gt_i32_e32 vcc, 27, v140
	s_nop 1
	v_cndmask_b32_e32 v63, v146, v63, vcc
	v_max3_f32 v48, v48, v62, v63
	v_max3_f32 v48, v48, v32, v33
	v_max3_f32 v48, v48, v34, v35
	v_max3_f32 v48, v48, v36, v37
	v_max3_f32 v48, v48, v38, v39
	v_max3_f32 v48, v48, v40, v41
	v_max3_f32 v48, v48, v42, v43
	v_max3_f32 v48, v48, v44, v45
	v_max3_f32 v48, v48, v46, v47
	v_max3_f32 v48, v48, v16, v17
	v_max3_f32 v48, v48, v18, v19
	v_max3_f32 v48, v48, v20, v21
	v_max3_f32 v48, v48, v22, v23
	v_max3_f32 v48, v48, v24, v25
	v_max3_f32 v48, v48, v26, v27
	v_max3_f32 v48, v48, v28, v29
	v_max3_f32 v48, v48, v30, v31
	v_max3_f32 v48, v48, v0, v1
	v_max3_f32 v48, v48, v2, v3
	v_max3_f32 v48, v48, v4, v5
	v_max3_f32 v48, v48, v6, v7
	v_max3_f32 v48, v48, v8, v9
	v_max3_f32 v48, v48, v10, v11
	v_max3_f32 v48, v48, v12, v13
	v_max3_f32 v48, v48, v14, v15
	v_max3_f32 v48, v48, v119, v115
	v_max3_f32 v48, v48, v116, v117
	v_max3_f32 v48, v48, v114, v68
	v_max3_f32 v48, v48, v67, v65
	v_max3_f32 v48, v48, v66, v64
	v_max3_f32 v48, v48, v57, v56
	v_cndmask_b32_e32 v52, v79, v146, vcc
	v_max3_f32 v48, v48, v53, v54
	v_max3_f32 v51, v48, v55, v52
	v_mbcnt_lo_u32_b32 v48, -1, 0
	v_mbcnt_hi_u32_b32 v49, -1, v48
	v_and_b32_e32 v50, 64, v49
	v_xor_b32_e32 v48, 32, v49
	v_add_u32_e32 v50, 64, v50
	v_cmp_lt_i32_e32 vcc, v48, v50
	s_nop 1
	v_cndmask_b32_e32 v48, v49, v48, vcc
	v_lshlrev_b32_e32 v48, 2, v48
	ds_bpermute_b32 v58, v48, v51
	v_cmp_gt_u32_e32 vcc, 32, v231
	s_waitcnt lgkmcnt(0)
	v_max_f32_e32 v58, v58, v58
	v_max_f32_e32 v58, v51, v58
	v_sub_f32_e32 v51, v121, v58
	v_exp_f32_e32 v74, v51
	v_sub_f32_e32 v77, v122, v58
	v_exp_f32_e32 v77, v77
	v_sub_f32_e32 v78, v123, v58
	v_exp_f32_e32 v78, v78
	v_sub_f32_e32 v79, v124, v58
	v_exp_f32_e32 v79, v79
	v_sub_f32_e32 v120, v125, v58
	v_add_f32_e32 v76, 0, v74
	v_exp_f32_e32 v120, v120
	v_sub_f32_e32 v121, v126, v58
	v_add_f32_e32 v76, v77, v76
	v_exp_f32_e32 v121, v121
	v_sub_f32_e32 v69, v69, v58
	v_add_f32_e32 v76, v78, v76
	v_exp_f32_e32 v69, v69
	v_sub_f32_e32 v70, v70, v58
	v_add_f32_e32 v76, v79, v76
	v_exp_f32_e32 v70, v70
	v_sub_f32_e32 v71, v71, v58
	v_add_f32_e32 v76, v120, v76
	v_exp_f32_e32 v71, v71
	v_sub_f32_e32 v72, v72, v58
	v_add_f32_e32 v76, v121, v76
	v_exp_f32_e32 v72, v72
	v_sub_f32_e32 v73, v73, v58
	v_add_f32_e32 v76, v69, v76
	v_exp_f32_e32 v73, v73
	v_sub_f32_e32 v59, v59, v58
	v_add_f32_e32 v76, v70, v76
	v_exp_f32_e32 v59, v59
	v_sub_f32_e32 v60, v60, v58
	v_add_f32_e32 v76, v71, v76
	v_exp_f32_e32 v60, v60
	v_sub_f32_e32 v61, v61, v58
	v_add_f32_e32 v76, v72, v76
	v_exp_f32_e32 v61, v61
	v_sub_f32_e32 v62, v62, v58
	v_add_f32_e32 v76, v73, v76
	v_exp_f32_e32 v62, v62
	v_sub_f32_e32 v63, v63, v58
	v_add_f32_e32 v76, v59, v76
	v_exp_f32_e32 v63, v63
	v_sub_f32_e32 v32, v32, v58
	v_add_f32_e32 v76, v60, v76
	v_exp_f32_e32 v122, v32
	v_sub_f32_e32 v33, v33, v58
	v_add_f32_e32 v32, v61, v76
	v_exp_f32_e32 v76, v33
	v_sub_f32_e32 v33, v34, v58
	v_add_f32_e32 v32, v62, v32
	v_exp_f32_e32 v123, v33
	v_sub_f32_e32 v33, v35, v58
	v_add_f32_e32 v32, v63, v32
	v_exp_f32_e32 v124, v33
	v_sub_f32_e32 v33, v36, v58
	v_add_f32_e32 v32, v122, v32
	v_exp_f32_e32 v125, v33
; #define LAS __attribute__((address_space(3)))
; __device__ __forceinline__ unsigned pk2(float lo, float hi) { return pg8::cvt_pk_bf16(lo, hi); }
; __device__ __forceinline__ void attn_unit(LAS unsigned char* lds, int unit, int mode, const bf16* QKVG, const float* sinks, const float* gain_a, bf16* MIX, float* SSA) {
;     ...
;         float sum = 0.f;
; #pragma unroll
;         for (int j = 0; j < 5; ++j)
; #pragma unroll
;             for (int r = 0; r < 16; ++r) { const float p = __builtin_amdgcn_exp2f(st[j][r] - mx); st[j][r] = p; sum += p; }
;         sum += __shfl_xor(sum, 32);
;         sum += __builtin_amdgcn_exp2f(sinkq - mx);
;         const float inv = __builtin_amdgcn_rcpf(sum);
;         f32x16 ot[2]; ot[0] = f32x16{}; ot[1] = f32x16{};
; #pragma unroll
;         for (int j = 0; j < 5; ++j)
; #pragma unroll
;             for (int s2 = 0; s2 < 2; ++s2) {
;                 v4u pw; pw.x = pk2(st[j][8 * s2 + 0], st[j][8 * s2 + 1]); pw.y = pk2(st[j][8 * s2 + 2], st[j][8 * s2 + 3]);
;                 pw.z = pk2(st[j][8 * s2 + 4], st[j][8 * s2 + 5]); pw.w = pk2(st[j][8 * s2 + 6], st[j][8 * s2 + 7]);
;                 const bf16x8 pf = __builtin_bit_cast(bf16x8, pw);
; #pragma unroll
;                 for (int db = 0; db < 2; ++db) {
;                     const bf16x8 vf = *(const LAS bf16x8*)(Vt + (db * 32 + q) * VP + 32 * (i + j) + 16 * s2 + 8 * hh);
;                     ot[db] = __builtin_amdgcn_mfma_f32_32x32x16_bf16(vf, pf, ot[db], 0, 0, 0);
;                 }
;             }
	v_sub_f32_e32 v33, v37, v58
	v_add_f32_e32 v32, v76, v32
	v_exp_f32_e32 v126, v33
	v_sub_f32_e32 v33, v38, v58
	v_add_f32_e32 v32, v123, v32
	v_exp_f32_e32 v127, v33
	v_sub_f32_e32 v33, v39, v58
	v_add_f32_e32 v32, v124, v32
	v_exp_f32_e32 v128, v33
	v_sub_f32_e32 v33, v40, v58
	v_add_f32_e32 v32, v125, v32
	v_exp_f32_e32 v129, v33
	v_sub_f32_e32 v33, v41, v58
	v_add_f32_e32 v32, v126, v32
	v_exp_f32_e32 v132, v33
	v_sub_f32_e32 v33, v42, v58
	v_lshl_add_u32 v51, v135, 1, v139
	v_add_f32_e32 v32, v127, v32
	v_exp_f32_e32 v139, v33
	v_sub_f32_e32 v33, v43, v58
	v_add_f32_e32 v32, v128, v32
	v_exp_f32_e32 v140, v33
	v_sub_f32_e32 v33, v44, v58
	v_add_f32_e32 v32, v129, v32
	v_exp_f32_e32 v141, v33
	v_sub_f32_e32 v33, v45, v58
	v_add_f32_e32 v32, v132, v32
	v_exp_f32_e32 v142, v33
	v_sub_f32_e32 v33, v46, v58
	v_add_f32_e32 v32, v139, v32
	v_exp_f32_e32 v143, v33
	v_sub_f32_e32 v33, v47, v58
	v_add_f32_e32 v32, v140, v32
	v_exp_f32_e32 v144, v33
	v_sub_f32_e32 v16, v16, v58
	v_add_f32_e32 v32, v141, v32
	v_exp_f32_e32 v145, v16
	v_sub_f32_e32 v17, v17, v58
	v_add_f32_e32 v16, v142, v32
	v_exp_f32_e32 v146, v17
	v_sub_f32_e32 v17, v18, v58
	v_add_f32_e32 v16, v143, v16
	v_exp_f32_e32 v147, v17
	v_sub_f32_e32 v17, v19, v58
	v_add_f32_e32 v16, v144, v16
	v_exp_f32_e32 v148, v17
	v_sub_f32_e32 v17, v20, v58
	v_add_f32_e32 v16, v145, v16
	v_exp_f32_e32 v150, v17
	v_sub_f32_e32 v17, v21, v58
	v_add_f32_e32 v16, v146, v16
	v_exp_f32_e32 v151, v17
	v_sub_f32_e32 v17, v22, v58
	v_add_f32_e32 v16, v147, v16
	v_exp_f32_e32 v152, v17
	v_sub_f32_e32 v17, v23, v58
	v_add_f32_e32 v16, v148, v16
	v_exp_f32_e32 v153, v17
	v_sub_f32_e32 v17, v24, v58
	v_add_f32_e32 v16, v150, v16
	v_exp_f32_e32 v154, v17
	v_sub_f32_e32 v17, v25, v58
	v_add_f32_e32 v16, v151, v16
	v_exp_f32_e32 v155, v17
	v_sub_f32_e32 v17, v26, v58
	v_add_f32_e32 v16, v152, v16
	v_exp_f32_e32 v156, v17
	v_sub_f32_e32 v17, v27, v58
	v_add_f32_e32 v16, v153, v16
	v_exp_f32_e32 v157, v17
	v_sub_f32_e32 v17, v28, v58
	v_add_f32_e32 v16, v154, v16
	v_exp_f32_e32 v158, v17
	v_sub_f32_e32 v17, v29, v58
	v_add_f32_e32 v16, v155, v16
	v_exp_f32_e32 v159, v17
	v_sub_f32_e32 v17, v30, v58
	v_add_f32_e32 v16, v156, v16
	v_exp_f32_e32 v172, v17
	v_sub_f32_e32 v17, v31, v58
	v_add_f32_e32 v16, v157, v16
	v_exp_f32_e32 v173, v17
	v_sub_f32_e32 v0, v0, v58
	v_add_f32_e32 v16, v158, v16
	v_exp_f32_e32 v174, v0
	v_sub_f32_e32 v1, v1, v58
	v_add_f32_e32 v0, v159, v16
	v_exp_f32_e32 v175, v1
	v_sub_f32_e32 v1, v2, v58
	v_add_f32_e32 v0, v172, v0
	v_exp_f32_e32 v176, v1
	v_sub_f32_e32 v1, v3, v58
	v_add_f32_e32 v0, v173, v0
	v_exp_f32_e32 v177, v1
	v_sub_f32_e32 v1, v4, v58
	v_add_f32_e32 v0, v174, v0
	v_exp_f32_e32 v178, v1
	v_add_f32_e32 v0, v175, v0
	v_add_f32_e32 v0, v176, v0
	v_add_f32_e32 v0, v177, v0
	v_add_f32_e32 v16, v178, v0
	v_sub_f32_e32 v0, v5, v58
	v_exp_f32_e32 v179, v0
	v_sub_f32_e32 v0, v6, v58
	v_exp_f32_e32 v180, v0
	v_sub_f32_e32 v17, v7, v58
	v_cvt_pk_bf16_f32 v0, v74, v77
	v_cvt_pk_bf16_f32 v1, v78, v79
	v_cvt_pk_bf16_f32 v2, v120, v121
	v_cvt_pk_bf16_f32 v3, v69, v70
	v_add3_u32 v69, v138, s0, v75
	v_sub_f32_e32 v8, v8, v58
	ds_read_b128 v[4:7], v69 offset:36864
	v_exp_f32_e32 v70, v17
	v_exp_f32_e32 v74, v8
	v_add_f32_e32 v8, v179, v16
	ds_read_b128 v[16:19], v69 offset:53760
	s_waitcnt lgkmcnt(1)
	v_mfma_f32_32x32x16_bf16 v[32:47], v[4:7], v[0:3], 0
	v_sub_f32_e32 v4, v9, v58
	v_exp_f32_e32 v78, v4
	v_cvt_pk_bf16_f32 v4, v71, v72
	v_cvt_pk_bf16_f32 v5, v73, v59
	v_cvt_pk_bf16_f32 v6, v60, v61
	v_cvt_pk_bf16_f32 v7, v62, v63
	ds_read_b128 v[60:63], v69 offset:36896
	s_waitcnt lgkmcnt(1)
	v_mfma_f32_32x32x16_bf16 v[16:31], v[16:19], v[0:3], 0
	v_sub_f32_e32 v0, v10, v58
	v_exp_f32_e32 v59, v0
	v_sub_f32_e32 v0, v11, v58
	v_exp_f32_e32 v71, v0
	v_sub_f32_e32 v0, v12, v58
	v_exp_f32_e32 v72, v0
	ds_read_b128 v[0:3], v69 offset:53792
	v_add_f32_e32 v8, v180, v8
	v_add_f32_e32 v8, v70, v8
	v_add_f32_e32 v77, v74, v8
	s_waitcnt lgkmcnt(0)
	v_mfma_f32_32x32x16_bf16 v[16:31], v[0:3], v[4:7], v[16:31]
	v_add_f32_e32 v0, v78, v77
	v_add_f32_e32 v0, v59, v0
	s_lshl_b32 s0, s17, 6
	v_add_f32_e32 v0, v71, v0
	v_add3_u32 v12, v138, s0, v75
	v_add_f32_e32 v73, v72, v0
	v_sub_f32_e32 v0, v13, v58
	v_mfma_f32_32x32x16_bf16 v[32:47], v[60:63], v[4:7], v[32:47]
	v_cvt_pk_bf16_f32 v8, v122, v76
	v_cvt_pk_bf16_f32 v9, v123, v124
	v_cvt_pk_bf16_f32 v10, v125, v126
	v_cvt_pk_bf16_f32 v11, v127, v128
	ds_read_b128 v[60:63], v12 offset:36864
	v_exp_f32_e32 v75, v0
	ds_read_b128 v[0:3], v12 offset:53760
	v_sub_f32_e32 v4, v14, v58
	v_exp_f32_e32 v76, v4
	s_waitcnt lgkmcnt(0)
	v_mfma_f32_32x32x16_bf16 v[16:31], v[0:3], v[8:11], v[16:31]
	v_add_f32_e32 v0, v75, v73
	v_cvt_pk_bf16_f32 v4, v129, v132
	v_cvt_pk_bf16_f32 v5, v139, v140
	v_cvt_pk_bf16_f32 v6, v141, v142
	v_cvt_pk_bf16_f32 v7, v143, v144
	v_add_u32_e32 v132, s15, v136
	s_lshl_b32 s0, s14, 1
	v_mfma_f32_32x32x16_bf16 v[32:47], v[60:63], v[8:11], v[32:47]
	v_add_f32_e32 v8, v76, v0
	v_sub_f32_e32 v0, v15, v58
	v_exp_f32_e32 v73, v0
	v_sub_f32_e32 v0, v119, v58
	ds_read_b128 v[60:63], v12 offset:36896
	v_exp_f32_e32 v77, v0
	ds_read_b128 v[0:3], v12 offset:53792
	s_waitcnt lgkmcnt(0)
	v_mfma_f32_32x32x16_bf16 v[16:31], v[0:3], v[4:7], v[16:31]
	v_sub_f32_e32 v0, v115, v58
	v_add_f32_e32 v8, v73, v8
	v_mfma_f32_32x32x16_bf16 v[32:47], v[60:63], v[4:7], v[32:47]
	v_exp_f32_e32 v61, v0
	v_sub_f32_e32 v0, v116, v58
	v_exp_f32_e32 v62, v0
	v_sub_f32_e32 v0, v117, v58
	v_add_f32_e32 v60, v77, v8
	v_cvt_pk_bf16_f32 v8, v145, v146
	v_cvt_pk_bf16_f32 v9, v147, v148
	v_cvt_pk_bf16_f32 v10, v150, v151
	v_cvt_pk_bf16_f32 v11, v152, v153
	ds_read_b128 v[12:15], v69 offset:36992
	v_exp_f32_e32 v63, v0
	ds_read_b128 v[0:3], v69 offset:53888
	v_sub_f32_e32 v4, v114, v58
	v_exp_f32_e32 v79, v4
	s_waitcnt lgkmcnt(0)
; #define LAS __attribute__((address_space(3)))
; __device__ __forceinline__ unsigned pk2(float lo, float hi) { return pg8::cvt_pk_bf16(lo, hi); }
; __device__ __forceinline__ float bflo(unsigned w) { return __uint_as_float(w << 16); }
; __device__ __forceinline__ float bfhi(unsigned w) { return __uint_as_float(w & 0xffff0000u); }
; __device__ __forceinline__ void attn_unit(LAS unsigned char* lds, int unit, int mode, const bf16* QKVG, const float* sinks, const float* gain_a, bf16* MIX, float* SSA) {
;     ...
;         sum += __shfl_xor(sum, 32);
;         sum += __builtin_amdgcn_exp2f(sinkq - mx);
;         const float inv = __builtin_amdgcn_rcpf(sum);
;         f32x16 ot[2]; ot[0] = f32x16{}; ot[1] = f32x16{};
; #pragma unroll
;         for (int j = 0; j < 5; ++j)
; #pragma unroll
;             for (int s2 = 0; s2 < 2; ++s2) {
;                 v4u pw; pw.x = pk2(st[j][8 * s2 + 0], st[j][8 * s2 + 1]); pw.y = pk2(st[j][8 * s2 + 2], st[j][8 * s2 + 3]);
;                 pw.z = pk2(st[j][8 * s2 + 4], st[j][8 * s2 + 5]); pw.w = pk2(st[j][8 * s2 + 6], st[j][8 * s2 + 7]);
;                 const bf16x8 pf = __builtin_bit_cast(bf16x8, pw);
; #pragma unroll
;                 for (int db = 0; db < 2; ++db) {
;                     const bf16x8 vf = *(const LAS bf16x8*)(Vt + (db * 32 + q) * VP + 32 * (i + j) + 16 * s2 + 8 * hh);
;                     ot[db] = __builtin_amdgcn_mfma_f32_32x32x16_bf16(vf, pf, ot[db], 0, 0, 0);
;                 }
;             }
;         float ss = 0.f;
; #pragma unroll
;         for (int k = 0; k < 4; ++k) *(LAS v4u*)(wt_row + 8 * k * KP) = grow[k];
; #pragma unroll
;         for (int e = 0; e < 8; ++e) gt[e] = *(const LAS v2u*)(wt_frd + 32 * (e >> 2) + 8 * (e & 3));
; #pragma unroll
;         for (int e = 0; e < 8; ++e) {
;             const int db = e >> 2, g4 = e & 3;
;             const float o0 = ot[db][4 * g4 + 0] * inv, o1 = ot[db][4 * g4 + 1] * inv, o2 = ot[db][4 * g4 + 2] * inv, o3 = ot[db][4 * g4 + 3] * inv;
;             ss += (o0 * o0 + o1 * o1) + (o2 * o2 + o3 * o3);
;             const f32x4 gn = *(const LAS f32x4*)(GN + 4 * hh + 32 * db + 8 * g4);
;             v2u z; z.x = pk2(o0 * gn[0] * silu(bflo(gt[e].x)), o1 * gn[1] * silu(bfhi(gt[e].x)));
;             z.y = pk2(o2 * gn[2] * silu(bflo(gt[e].y)), o3 * gn[3] * silu(bfhi(gt[e].y)));
;             *(LAS v2u*)(wt_frd + 32 * db + 8 * g4) = z;
;         }
	v_mfma_f32_32x32x16_bf16 v[16:31], v[0:3], v[8:11], v[16:31]
	v_add_f32_e32 v0, v61, v60
	v_add_f32_e32 v0, v62, v0
	v_add_f32_e32 v0, v63, v0
	v_add_f32_e32 v60, v79, v0
	v_sub_f32_e32 v0, v68, v58
	v_cvt_pk_bf16_f32 v4, v154, v155
	v_cvt_pk_bf16_f32 v5, v156, v157
	v_mfma_f32_32x32x16_bf16 v[32:47], v[12:15], v[8:11], v[32:47]
	v_cvt_pk_bf16_f32 v6, v158, v159
	v_cvt_pk_bf16_f32 v7, v172, v173
	ds_read_b128 v[12:15], v69 offset:37024
	v_exp_f32_e32 v68, v0
	ds_read_b128 v[0:3], v69 offset:53920
	v_sub_f32_e32 v8, v67, v58
	v_exp_f32_e32 v67, v8
	s_waitcnt lgkmcnt(0)
	v_mfma_f32_32x32x16_bf16 v[16:31], v[0:3], v[4:7], v[16:31]
	v_add_f32_e32 v0, v68, v60
	v_add_f32_e32 v60, v67, v0
	v_sub_f32_e32 v0, v65, v58
	v_exp_f32_e32 v65, v0
	v_sub_f32_e32 v0, v66, v58
	v_cvt_pk_bf16_f32 v8, v174, v175
	v_cvt_pk_bf16_f32 v9, v176, v177
	v_mfma_f32_32x32x16_bf16 v[32:47], v[12:15], v[4:7], v[32:47]
	v_cvt_pk_bf16_f32 v10, v178, v179
	v_cvt_pk_bf16_f32 v11, v180, v70
	ds_read_b128 v[12:15], v69 offset:37056
	v_exp_f32_e32 v66, v0
	ds_read_b128 v[0:3], v69 offset:53952
	v_sub_f32_e32 v4, v64, v58
	v_exp_f32_e32 v64, v4
	s_waitcnt lgkmcnt(0)
	v_mfma_f32_32x32x16_bf16 v[16:31], v[0:3], v[8:11], v[16:31]
	v_sub_f32_e32 v0, v57, v58
	v_exp_f32_e32 v57, v0
	v_add_f32_e32 v0, v65, v60
	v_add_f32_e32 v0, v66, v0
	v_add_f32_e32 v0, v64, v0
	v_cvt_pk_bf16_f32 v4, v74, v78
	v_cvt_pk_bf16_f32 v5, v59, v71
	v_mfma_f32_32x32x16_bf16 v[32:47], v[12:15], v[8:11], v[32:47]
	v_cvt_pk_bf16_f32 v6, v72, v75
	v_cvt_pk_bf16_f32 v7, v76, v73
	ds_read_b128 v[12:15], v69 offset:37088
	v_add_f32_e32 v59, v57, v0
	ds_read_b128 v[0:3], v69 offset:53984
	v_sub_f32_e32 v8, v56, v58
	v_exp_f32_e32 v56, v8
	s_waitcnt lgkmcnt(0)
	v_mfma_f32_32x32x16_bf16 v[16:31], v[0:3], v[4:7], v[16:31]
	v_sub_f32_e32 v0, v53, v58
	v_exp_f32_e32 v53, v0
	v_sub_f32_e32 v0, v54, v58
	v_exp_f32_e32 v54, v0
	v_sub_f32_e32 v0, v55, v58
	v_cvt_pk_bf16_f32 v8, v77, v61
	v_cvt_pk_bf16_f32 v9, v62, v63
	v_mfma_f32_32x32x16_bf16 v[32:47], v[12:15], v[4:7], v[32:47]
	v_cvt_pk_bf16_f32 v10, v79, v68
	v_cvt_pk_bf16_f32 v11, v67, v65
	ds_read_b128 v[12:15], v69 offset:37120
	v_exp_f32_e32 v55, v0
	ds_read_b128 v[0:3], v69 offset:54016
	v_sub_f32_e32 v4, v52, v58
	v_exp_f32_e32 v52, v4
	s_waitcnt lgkmcnt(0)
	v_mfma_f32_32x32x16_bf16 v[16:31], v[0:3], v[8:11], v[16:31]
	v_add_f32_e32 v0, v56, v59
	v_cvt_pk_bf16_f32 v4, v66, v64
	v_cvt_pk_bf16_f32 v5, v57, v56
	v_cvt_pk_bf16_f32 v6, v53, v54
	v_cvt_pk_bf16_f32 v7, v55, v52
	v_add_f32_e32 v0, v53, v0
	v_add_f32_e32 v0, v54, v0
	v_mfma_f32_32x32x16_bf16 v[32:47], v[12:15], v[8:11], v[32:47]
	ds_read_b128 v[12:15], v69 offset:37152
	v_add_f32_e32 v0, v55, v0
	v_add_f32_e32 v8, v52, v0
	ds_read_b128 v[0:3], v69 offset:54048
	ds_bpermute_b32 v9, v48, v8
	v_sub_f32_e32 v10, v118, v58
	v_exp_f32_e32 v10, v10
	s_waitcnt lgkmcnt(2)
	v_mfma_f32_32x32x16_bf16 v[32:47], v[12:15], v[4:7], v[32:47]
	s_waitcnt lgkmcnt(0)
	v_add_f32_e32 v8, v8, v9
	v_add_f32_e32 v8, v10, v8
	s_waitcnt vmcnt(7)
	ds_write_b128 v137, v[98:101]
	s_waitcnt vmcnt(2)
	ds_write_b128 v137, v[102:105] offset:1152
	s_waitcnt vmcnt(1)
	ds_write_b128 v137, v[106:109] offset:2304
	s_waitcnt vmcnt(0)
	ds_write_b128 v137, v[110:113] offset:3456
	v_rcp_f32_e32 v53, v8
	v_lshl_add_u32 v52, v135, 2, s16
	v_mul_f32_e32 v13, v32, v53
	v_mfma_f32_32x32x16_bf16 v[16:31], v[0:3], v[4:7], v[16:31]
	ds_read2_b64 v[54:57], v51 offset1:2
	ds_read2_b64 v[8:11], v51 offset0:4 offset1:6
	ds_read2_b64 v[4:7], v51 offset0:8 offset1:10
	ds_read2_b64 v[0:3], v51 offset0:12 offset1:14
	v_mul_f32_e32 v59, v33, v53
	s_waitcnt lgkmcnt(3)
	v_lshlrev_b32_e32 v12, 16, v54
	v_mul_f32_e32 v58, 0xbfb8aa3b, v12
	v_exp_f32_e32 v60, v58
	v_and_b32_e32 v58, 0xffff0000, v54
	v_mul_f32_e32 v61, v34, v53
	v_mul_f32_e32 v63, v35, v53
	ds_read_b128 v[32:35], v52
	v_mul_f32_e32 v54, 0xbfb8aa3b, v58
	v_exp_f32_e32 v54, v54
	v_add_f32_e32 v60, 1.0, v60
	v_rcp_f32_e32 v64, v60
	s_waitcnt lgkmcnt(0)
	v_mov_b32_e32 v65, v32
	v_add_f32_e32 v32, 1.0, v54
	v_rcp_f32_e32 v32, v32
	v_lshlrev_b32_e32 v60, 16, v55
	v_and_b32_e32 v62, 0xffff0000, v55
	v_pk_mul_f32 v[64:65], v[64:65], v[12:13]
	v_pk_mul_f32 v[32:33], v[32:33], v[58:59]
	v_mul_f32_e32 v12, v64, v65
	v_mul_f32_e32 v54, v32, v33
	v_mul_f32_e32 v32, 0xbfb8aa3b, v60
	v_exp_f32_e32 v32, v32
	v_mul_f32_e32 v33, 0xbfb8aa3b, v62
	v_exp_f32_e32 v55, v33
	v_mov_b32_e32 v33, v34
	v_add_f32_e32 v32, 1.0, v32
	v_rcp_f32_e32 v32, v32
	v_add_f32_e32 v34, 1.0, v55
	v_rcp_f32_e32 v34, v34
	v_cvt_pk_bf16_f32 v54, v12, v54
	v_pk_mul_f32 v[32:33], v[32:33], v[60:61]
	v_mul_f32_e32 v15, v63, v63
	v_mul_f32_e32 v12, v32, v33
	v_pk_mul_f32 v[32:33], v[34:35], v[62:63]
	v_fmac_f32_e32 v15, v61, v61
	v_mul_f32_e32 v32, v32, v33
	v_cvt_pk_bf16_f32 v55, v12, v32
	ds_write_b64 v51, v[54:55]
	v_lshlrev_b32_e32 v54, 16, v56
	v_mul_f32_e32 v55, v36, v53
	v_mul_f32_e32 v36, 0xbfb8aa3b, v54
	v_exp_f32_e32 v58, v36
	v_and_b32_e32 v36, 0xffff0000, v56
	ds_read_b128 v[32:35], v52 offset:32
	v_mul_f32_e32 v56, 0xbfb8aa3b, v36
	v_exp_f32_e32 v56, v56
	v_mul_f32_e32 v37, v37, v53
	v_mul_f32_e32 v39, v39, v53
	s_waitcnt lgkmcnt(0)
; #define LAS __attribute__((address_space(3)))
; __device__ __forceinline__ unsigned pk2(float lo, float hi) { return pg8::cvt_pk_bf16(lo, hi); }
; __device__ __forceinline__ float bflo(unsigned w) { return __uint_as_float(w << 16); }
; __device__ __forceinline__ float bfhi(unsigned w) { return __uint_as_float(w & 0xffff0000u); }
; __device__ __forceinline__ float silu(float g) { return g * __builtin_amdgcn_rcpf(1.0f + __builtin_amdgcn_exp2f(-1.4426950408889634f * g)); }
; __device__ __forceinline__ void attn_unit(LAS unsigned char* lds, int unit, int mode, const bf16* QKVG, const float* sinks, const float* gain_a, bf16* MIX, float* SSA) {
;     ...
;         float ss = 0.f;
; #pragma unroll
;         for (int k = 0; k < 4; ++k) *(LAS v4u*)(wt_row + 8 * k * KP) = grow[k];
; #pragma unroll
;         for (int e = 0; e < 8; ++e) gt[e] = *(const LAS v2u*)(wt_frd + 32 * (e >> 2) + 8 * (e & 3));
; #pragma unroll
;         for (int e = 0; e < 8; ++e) {
;             const int db = e >> 2, g4 = e & 3;
;             const float o0 = ot[db][4 * g4 + 0] * inv, o1 = ot[db][4 * g4 + 1] * inv, o2 = ot[db][4 * g4 + 2] * inv, o3 = ot[db][4 * g4 + 3] * inv;
;             ss += (o0 * o0 + o1 * o1) + (o2 * o2 + o3 * o3);
;             const f32x4 gn = *(const LAS f32x4*)(GN + 4 * hh + 32 * db + 8 * g4);
;             v2u z; z.x = pk2(o0 * gn[0] * silu(bflo(gt[e].x)), o1 * gn[1] * silu(bfhi(gt[e].x)));
;             z.y = pk2(o2 * gn[2] * silu(bflo(gt[e].y)), o3 * gn[3] * silu(bfhi(gt[e].y)));
;             *(LAS v2u*)(wt_frd + 32 * db + 8 * g4) = z;
;         }
	v_mov_b32_e32 v61, v32
	v_add_f32_e32 v32, 1.0, v56
	v_rcp_f32_e32 v32, v32
	v_mul_f32_e32 v14, v59, v59
	v_mul_f32_e32 v59, v38, v53
	v_mul_f32_e32 v12, v37, v37
	v_mul_f32_e32 v38, v39, v39
	v_add_f32_e32 v58, 1.0, v58
	v_fmac_f32_e32 v12, v55, v55
	v_fmac_f32_e32 v38, v59, v59
	v_rcp_f32_e32 v60, v58
	v_pk_mul_f32 v[32:33], v[32:33], v[36:37]
	v_lshlrev_b32_e32 v58, 16, v57
	v_add_f32_e32 v12, v12, v38
	v_mul_f32_e32 v36, v32, v33
	v_mul_f32_e32 v32, 0xbfb8aa3b, v58
	v_and_b32_e32 v38, 0xffff0000, v57
	v_exp_f32_e32 v32, v32
	v_mul_f32_e32 v33, 0xbfb8aa3b, v38
	v_exp_f32_e32 v37, v33
	v_mov_b32_e32 v33, v34
	v_add_f32_e32 v32, 1.0, v32
	v_rcp_f32_e32 v32, v32
	v_add_f32_e32 v34, 1.0, v37
	v_rcp_f32_e32 v34, v34
	v_pk_mul_f32 v[54:55], v[60:61], v[54:55]
	v_pk_mul_f32 v[32:33], v[32:33], v[58:59]
	v_mul_f32_e32 v54, v54, v55
	v_cvt_pk_bf16_f32 v36, v54, v36
	v_mul_f32_e32 v37, v32, v33
	v_pk_mul_f32 v[32:33], v[34:35], v[38:39]
	v_mul_f32_e32 v39, v41, v53
	v_mul_f32_e32 v32, v32, v33
	v_cvt_pk_bf16_f32 v37, v37, v32
	ds_write_b64 v51, v[36:37] offset:16
	v_lshlrev_b32_e32 v36, 16, v8
	v_mul_f32_e32 v38, 0xbfb8aa3b, v36
	v_exp_f32_e32 v54, v38
	v_and_b32_e32 v38, 0xffff0000, v8
	v_mul_f32_e32 v8, 0xbfb8aa3b, v38
	ds_read_b128 v[32:35], v52 offset:64
	v_exp_f32_e32 v8, v8
	v_mul_f32_e32 v43, v43, v53
	v_mul_f32_e32 v37, v40, v53
	v_mul_f32_e32 v41, v42, v53
	v_add_f32_e32 v8, 1.0, v8
	v_mul_f32_e32 v40, v39, v39
	v_mul_f32_e32 v42, v43, v43
	s_waitcnt lgkmcnt(0)
	v_mov_b32_e32 v55, v32
	v_rcp_f32_e32 v32, v8
	v_fmac_f32_e32 v40, v37, v37
	v_fmac_f32_e32 v42, v41, v41
	v_add_f32_e32 v56, v40, v42
	v_lshlrev_b32_e32 v40, 16, v9
	v_mul_f32_e32 v8, 0xbfb8aa3b, v40
	v_and_b32_e32 v42, 0xffff0000, v9
	v_pk_mul_f32 v[32:33], v[32:33], v[38:39]
	v_exp_f32_e32 v8, v8
	v_mul_f32_e32 v9, 0xbfb8aa3b, v42
	v_mul_f32_e32 v32, v32, v33
	v_exp_f32_e32 v33, v9
	v_add_f32_e32 v8, 1.0, v8
	v_rcp_f32_e32 v8, v8
	v_add_f32_e32 v54, 1.0, v54
	v_add_f32_e32 v33, 1.0, v33
	v_mov_b32_e32 v9, v34
	v_rcp_f32_e32 v34, v33
	v_rcp_f32_e32 v54, v54
	v_pk_mul_f32 v[8:9], v[8:9], v[40:41]
	v_mul_f32_e32 v41, v47, v53
	v_mul_f32_e32 v33, v8, v9
	v_pk_mul_f32 v[8:9], v[34:35], v[42:43]
	v_pk_mul_f32 v[36:37], v[54:55], v[36:37]
	v_mul_f32_e32 v8, v8, v9
	v_mul_f32_e32 v36, v36, v37
	v_cvt_pk_bf16_f32 v32, v36, v32
	v_cvt_pk_bf16_f32 v33, v33, v8
	v_lshlrev_b32_e32 v8, 16, v10
	v_mul_f32_e32 v36, 0xbfb8aa3b, v8
	v_exp_f32_e32 v42, v36
	v_and_b32_e32 v36, 0xffff0000, v10
	ds_write_b64 v51, v[32:33] offset:32
	v_mul_f32_e32 v10, 0xbfb8aa3b, v36
	ds_read_b128 v[32:35], v52 offset:96
	v_exp_f32_e32 v10, v10
	v_add_f32_e32 v42, 1.0, v42
	v_rcp_f32_e32 v42, v42
	v_mul_f32_e32 v37, v45, v53
	v_add_f32_e32 v10, 1.0, v10
	s_waitcnt lgkmcnt(0)
	v_mov_b32_e32 v43, v32
	v_rcp_f32_e32 v32, v10
	v_mul_f32_e32 v9, v44, v53
	v_mul_f32_e32 v39, v46, v53
	v_mul_f32_e32 v38, v37, v37
	v_mul_f32_e32 v40, v41, v41
	v_fmac_f32_e32 v38, v9, v9
	v_fmac_f32_e32 v40, v39, v39
	v_pk_mul_f32 v[8:9], v[42:43], v[8:9]
	v_add_f32_e32 v44, v38, v40
	v_mul_f32_e32 v10, v8, v9
	v_pk_mul_f32 v[8:9], v[32:33], v[36:37]
	v_lshlrev_b32_e32 v38, 16, v11
	v_mul_f32_e32 v32, v8, v9
	v_mul_f32_e32 v8, 0xbfb8aa3b, v38
	v_and_b32_e32 v40, 0xffff0000, v11
	v_exp_f32_e32 v8, v8
	v_mul_f32_e32 v9, 0xbfb8aa3b, v40
	v_exp_f32_e32 v11, v9
	v_mov_b32_e32 v9, v34
	v_add_f32_e32 v8, 1.0, v8
	v_rcp_f32_e32 v8, v8
	v_add_f32_e32 v11, 1.0, v11
	v_rcp_f32_e32 v34, v11
	v_cvt_pk_bf16_f32 v10, v10, v32
	v_lshlrev_b32_e32 v32, 16, v4
	v_pk_mul_f32 v[8:9], v[8:9], v[38:39]
	v_mul_f32_e32 v33, v16, v53
	v_mul_f32_e32 v16, 0xbfb8aa3b, v32
	v_mul_f32_e32 v11, v8, v9
	v_pk_mul_f32 v[8:9], v[34:35], v[40:41]
	v_exp_f32_e32 v36, v16
	v_and_b32_e32 v16, 0xffff0000, v4
	v_mul_f32_e32 v8, v8, v9
	v_cvt_pk_bf16_f32 v11, v11, v8
	ds_write_b64 v51, v[10:11] offset:48
	v_mul_f32_e32 v4, 0xbfb8aa3b, v16
	ds_read_b128 v[8:11], v52 offset:128
	v_exp_f32_e32 v4, v4
	v_mul_f32_e32 v17, v17, v53
	v_mul_f32_e32 v19, v19, v53
	v_mul_f32_e32 v35, v18, v53
	v_add_f32_e32 v4, 1.0, v4
	v_mul_f32_e32 v18, v17, v17
	v_mul_f32_e32 v34, v19, v19
	s_waitcnt lgkmcnt(0)
	v_mov_b32_e32 v37, v8
	v_rcp_f32_e32 v8, v4
	v_fmac_f32_e32 v18, v33, v33
	v_fmac_f32_e32 v34, v35, v35
	v_add_f32_e32 v38, v18, v34
	v_lshlrev_b32_e32 v34, 16, v5
	v_mul_f32_e32 v4, 0xbfb8aa3b, v34
	v_and_b32_e32 v18, 0xffff0000, v5
	v_pk_mul_f32 v[8:9], v[8:9], v[16:17]
	v_exp_f32_e32 v4, v4
	v_mul_f32_e32 v5, 0xbfb8aa3b, v18
	v_mul_f32_e32 v8, v8, v9
	v_exp_f32_e32 v9, v5
	v_add_f32_e32 v4, 1.0, v4
	v_rcp_f32_e32 v4, v4
	v_add_f32_e32 v36, 1.0, v36
	v_add_f32_e32 v9, 1.0, v9
	v_mov_b32_e32 v5, v10
	v_rcp_f32_e32 v10, v9
	v_rcp_f32_e32 v36, v36
	v_pk_mul_f32 v[4:5], v[4:5], v[34:35]
	v_mul_f32_e32 v17, v21, v53
	v_mul_f32_e32 v9, v4, v5
	v_pk_mul_f32 v[4:5], v[10:11], v[18:19]
	v_pk_mul_f32 v[32:33], v[36:37], v[32:33]
	v_mul_f32_e32 v4, v4, v5
	v_mul_f32_e32 v32, v32, v33
	v_cvt_pk_bf16_f32 v8, v32, v8
	v_cvt_pk_bf16_f32 v9, v9, v4
	v_lshlrev_b32_e32 v4, 16, v6
	v_mul_f32_e32 v16, 0xbfb8aa3b, v4
	v_mul_f32_e32 v19, v22, v53
	v_exp_f32_e32 v22, v16
	v_and_b32_e32 v16, 0xffff0000, v6
	ds_write_b64 v51, v[8:9] offset:64
	v_mul_f32_e32 v6, 0xbfb8aa3b, v16
	ds_read_b128 v[8:11], v52 offset:160
	v_exp_f32_e32 v6, v6
	v_add_f32_e32 v22, 1.0, v22
	v_rcp_f32_e32 v22, v22
	v_mul_f32_e32 v21, v23, v53
	v_add_f32_e32 v6, 1.0, v6
	s_waitcnt lgkmcnt(0)
; #define LAS __attribute__((address_space(3)))
; __device__ __forceinline__ unsigned pk2(float lo, float hi) { return pg8::cvt_pk_bf16(lo, hi); }
; __device__ __forceinline__ float bflo(unsigned w) { return __uint_as_float(w << 16); }
; __device__ __forceinline__ float bfhi(unsigned w) { return __uint_as_float(w & 0xffff0000u); }
; __device__ __forceinline__ float silu(float g) { return g * __builtin_amdgcn_rcpf(1.0f + __builtin_amdgcn_exp2f(-1.4426950408889634f * g)); }
; __device__ __forceinline__ void attn_unit(LAS unsigned char* lds, int unit, int mode, const bf16* QKVG, const float* sinks, const float* gain_a, bf16* MIX, float* SSA) {
;     ...
;         for (int e = 0; e < 8; ++e) {
;             const int db = e >> 2, g4 = e & 3;
;             const float o0 = ot[db][4 * g4 + 0] * inv, o1 = ot[db][4 * g4 + 1] * inv, o2 = ot[db][4 * g4 + 2] * inv, o3 = ot[db][4 * g4 + 3] * inv;
;             ss += (o0 * o0 + o1 * o1) + (o2 * o2 + o3 * o3);
;             const f32x4 gn = *(const LAS f32x4*)(GN + 4 * hh + 32 * db + 8 * g4);
;             v2u z; z.x = pk2(o0 * gn[0] * silu(bflo(gt[e].x)), o1 * gn[1] * silu(bfhi(gt[e].x)));
;             z.y = pk2(o2 * gn[2] * silu(bflo(gt[e].y)), o3 * gn[3] * silu(bfhi(gt[e].y)));
;             *(LAS v2u*)(wt_frd + 32 * db + 8 * g4) = z;
;         }
;         {
;             bf16* orow0 = MIX + (size_t)(T0 + 32 * i + r8) * DMIX + 1024 + h * 64 + 8 * c8;
; #pragma unroll
;             for (int k = 0; k < 4; ++k) { const v4u v = *(const LAS v4u*)(wt_row + 8 * k * KP); *(v4u*)(orow0 + (size_t)(8 * k) * DMIX) = v; }
;         }
; #pragma unroll
;         for (int k = 0; k < 4; ++k) *(LAS v4u*)(wt_row + 8 * k * KP) = qrow[k];
;         ss += __shfl_xor(ss, 32);
;         if (hh == 0) SS[w * 128 + 32 * i + q] = ss;
	v_mov_b32_e32 v23, v8
	v_rcp_f32_e32 v8, v6
	v_mul_f32_e32 v5, v20, v53
	v_mul_f32_e32 v18, v17, v17
	v_mul_f32_e32 v20, v21, v21
	v_fmac_f32_e32 v18, v5, v5
	v_fmac_f32_e32 v20, v19, v19
	v_pk_mul_f32 v[4:5], v[22:23], v[4:5]
	v_add_f32_e32 v32, v18, v20
	v_mul_f32_e32 v6, v4, v5
	v_pk_mul_f32 v[4:5], v[8:9], v[16:17]
	v_lshlrev_b32_e32 v18, 16, v7
	v_mul_f32_e32 v8, v4, v5
	v_mul_f32_e32 v4, 0xbfb8aa3b, v18
	v_and_b32_e32 v20, 0xffff0000, v7
	v_exp_f32_e32 v4, v4
	v_mul_f32_e32 v5, 0xbfb8aa3b, v20
	v_exp_f32_e32 v7, v5
	v_mov_b32_e32 v5, v10
	v_add_f32_e32 v4, 1.0, v4
	v_rcp_f32_e32 v4, v4
	v_add_f32_e32 v7, 1.0, v7
	v_rcp_f32_e32 v10, v7
	v_cvt_pk_bf16_f32 v6, v6, v8
	v_pk_mul_f32 v[4:5], v[4:5], v[18:19]
	v_lshlrev_b32_e32 v8, 16, v0
	v_mul_f32_e32 v7, v4, v5
	v_pk_mul_f32 v[4:5], v[10:11], v[20:21]
	v_mul_f32_e32 v10, 0xbfb8aa3b, v8
	v_exp_f32_e32 v20, v10
	v_and_b32_e32 v10, 0xffff0000, v0
	v_mul_f32_e32 v4, v4, v5
	v_cvt_pk_bf16_f32 v7, v7, v4
	ds_write_b64 v51, v[6:7] offset:80
	v_mul_f32_e32 v0, 0xbfb8aa3b, v10
	ds_read_b128 v[4:7], v52 offset:192
	v_exp_f32_e32 v0, v0
	v_mul_f32_e32 v11, v25, v53
	v_mul_f32_e32 v19, v27, v53
	v_mul_f32_e32 v9, v24, v53
	v_add_f32_e32 v0, 1.0, v0
	v_mul_f32_e32 v17, v26, v53
	v_mul_f32_e32 v16, v11, v11
	v_mul_f32_e32 v18, v19, v19
	s_waitcnt lgkmcnt(0)
	v_mov_b32_e32 v21, v4
	v_rcp_f32_e32 v4, v0
	v_fmac_f32_e32 v16, v9, v9
	v_fmac_f32_e32 v18, v17, v17
	v_add_f32_e32 v22, v16, v18
	v_lshlrev_b32_e32 v16, 16, v1
	v_mul_f32_e32 v0, 0xbfb8aa3b, v16
	v_and_b32_e32 v18, 0xffff0000, v1
	v_pk_mul_f32 v[4:5], v[4:5], v[10:11]
	v_exp_f32_e32 v0, v0
	v_mul_f32_e32 v1, 0xbfb8aa3b, v18
	v_mul_f32_e32 v4, v4, v5
	v_exp_f32_e32 v5, v1
	v_add_f32_e32 v0, 1.0, v0
	v_rcp_f32_e32 v0, v0
	v_add_f32_e32 v20, 1.0, v20
	v_add_f32_e32 v5, 1.0, v5
	v_mov_b32_e32 v1, v6
	v_rcp_f32_e32 v6, v5
	v_rcp_f32_e32 v20, v20
	v_pk_mul_f32 v[0:1], v[0:1], v[16:17]
	v_mul_f32_e32 v17, v31, v53
	v_mul_f32_e32 v5, v0, v1
	v_pk_mul_f32 v[0:1], v[6:7], v[18:19]
	v_pk_mul_f32 v[8:9], v[20:21], v[8:9]
	v_mul_f32_e32 v0, v0, v1
	v_mul_f32_e32 v8, v8, v9
	v_cvt_pk_bf16_f32 v4, v8, v4
	v_cvt_pk_bf16_f32 v5, v5, v0
	v_lshlrev_b32_e32 v0, 16, v2
	v_mul_f32_e32 v8, 0xbfb8aa3b, v0
	v_exp_f32_e32 v18, v8
	v_and_b32_e32 v8, 0xffff0000, v2
	ds_write_b64 v51, v[4:5] offset:96
	v_mul_f32_e32 v2, 0xbfb8aa3b, v8
	ds_read_b128 v[4:7], v52 offset:224
	v_exp_f32_e32 v2, v2
	v_add_f32_e32 v18, 1.0, v18
	v_rcp_f32_e32 v18, v18
	v_mul_f32_e32 v9, v29, v53
	v_add_f32_e32 v2, 1.0, v2
	s_waitcnt lgkmcnt(0)
	v_mov_b32_e32 v19, v4
	v_rcp_f32_e32 v4, v2
	v_mul_f32_e32 v1, v28, v53
	v_mul_f32_e32 v11, v30, v53
	v_mul_f32_e32 v10, v9, v9
	v_mul_f32_e32 v16, v17, v17
	v_fmac_f32_e32 v10, v1, v1
	v_fmac_f32_e32 v16, v11, v11
	v_pk_mul_f32 v[0:1], v[18:19], v[0:1]
	v_add_f32_e32 v20, v10, v16
	v_mul_f32_e32 v2, v0, v1
	v_pk_mul_f32 v[0:1], v[4:5], v[8:9]
	v_lshlrev_b32_e32 v10, 16, v3
	v_mul_f32_e32 v4, v0, v1
	v_mul_f32_e32 v0, 0xbfb8aa3b, v10
	v_and_b32_e32 v16, 0xffff0000, v3
	v_exp_f32_e32 v0, v0
	v_mul_f32_e32 v1, 0xbfb8aa3b, v16
	v_exp_f32_e32 v3, v1
	v_mov_b32_e32 v1, v6
	v_add_f32_e32 v0, 1.0, v0
	v_rcp_f32_e32 v0, v0
	v_add_f32_e32 v3, 1.0, v3
	v_rcp_f32_e32 v6, v3
	v_cvt_pk_bf16_f32 v2, v2, v4
	v_pk_mul_f32 v[0:1], v[0:1], v[10:11]
	v_fmac_f32_e32 v14, v13, v13
	v_mul_f32_e32 v3, v0, v1
	v_pk_mul_f32 v[0:1], v[6:7], v[16:17]
	s_nop 0
	v_mul_f32_e32 v0, v0, v1
	v_cvt_pk_bf16_f32 v3, v3, v0
	ds_write_b64 v51, v[2:3] offset:112
	v_lshlrev_b64 v[0:1], 12, v[132:133]
	v_lshl_add_u64 v[4:5], s[94:95], 0, v[0:1]
	ds_read_b128 v[0:3], v137
	v_lshl_add_u64 v[4:5], v[4:5], 0, s[0:1]
	v_lshl_add_u64 v[8:9], v[130:131], 1, v[4:5]
	ds_read_b128 v[4:7], v137 offset:1152
	s_mov_b32 s0, 0x8000
	s_waitcnt lgkmcnt(1)
	global_store_dwordx4 v[8:9], v[0:3], off offset:2048
	s_nop 1
	v_add_co_u32_e64 v0, s[4:5], s0, v8
	s_mov_b32 s0, 0x10000
	s_nop 0
	v_addc_co_u32_e64 v1, s[4:5], 0, v9, s[4:5]
	s_waitcnt lgkmcnt(0)
	global_store_dwordx4 v[0:1], v[4:7], off offset:2048
	ds_read_b128 v[0:3], v137 offset:2304
	ds_read_b128 v[4:7], v137 offset:3456
	v_add_co_u32_e64 v10, s[4:5], s0, v8
	s_mov_b32 s0, 0x18000
	s_nop 0
	v_addc_co_u32_e64 v11, s[4:5], 0, v9, s[4:5]
	s_waitcnt lgkmcnt(1)
	global_store_dwordx4 v[10:11], v[0:3], off offset:2048
	s_nop 1
	v_add_co_u32_e64 v0, s[4:5], s0, v8
	s_nop 1
	v_addc_co_u32_e64 v1, s[4:5], 0, v9, s[4:5]
	s_waitcnt lgkmcnt(0)
	global_store_dwordx4 v[0:1], v[4:7], off offset:2048
	v_add_f32_e32 v0, v14, v15
	v_add_f32_e32 v0, v0, v12
	v_add_f32_e32 v0, v56, v0
	v_add_f32_e32 v0, v44, v0
	v_add_f32_e32 v0, v38, v0
	v_add_f32_e32 v0, v32, v0
	v_add_f32_e32 v0, v22, v0
	v_add_f32_e32 v0, v20, v0
	ds_bpermute_b32 v1, v48, v0
	ds_write_b128 v137, v[82:85]
	ds_write_b128 v137, v[86:89] offset:1152
	ds_write_b128 v137, v[90:93] offset:2304
	ds_write_b128 v137, v[94:97] offset:3456
	s_and_saveexec_b64 s[0:1], vcc
	s_cbranch_execz .LBB0_311
	s_lshl_b32 s3, s13, 9
	s_add_i32 s3, s3, 0
	s_lshl_b32 s4, s15, 2
	s_add_i32 s3, s3, s4
	s_waitcnt lgkmcnt(4)
	v_add_f32_e32 v0, v0, v1
	v_lshl_add_u32 v1, v134, 2, s3
	v_add_u32_e32 v1, 0x11400, v1
	ds_write_b32 v1, v0

; __device__ __forceinline__ unsigned xb_ld(unsigned* p)              { return __hip_atomic_load(p, __ATOMIC_RELAXED, __HIP_MEMORY_SCOPE_AGENT); }
; __device__ __forceinline__ void group_wait(unsigned* cnt, unsigned want, unsigned* bar) {
;     if (threadIdx.x == 0) {
;         unsigned sp = 0;
;         while (__hip_atomic_load(cnt, __ATOMIC_RELAXED, __HIP_MEMORY_SCOPE_AGENT) < want) {
;             __builtin_amdgcn_s_sleep(2);
;             if ((++sp & 255u) == 0u) { if (xb_ld(&bar[XB_TMO])) break; if (sp > XB_SPIN_CAP) { atomicAdd(&bar[XB_TMO], 1u); break; } }
;         }
;         __builtin_amdgcn_fence(__ATOMIC_ACQUIRE, "agent");
;         asm volatile("s_waitcnt vmcnt(0)" ::: "memory");
;     }
; __global__ void __launch_bounds__(NWAVES * 64, 2) fwd_megakernel(Args a) {
;     ...
;             if (l >= 24) {
;                 group_wait(gcc, 32u, (unsigned*)(ws + WS_BAR));
;                 if (l != 24 && wave < 2) conv_fixup(2 * (gb * 8 + (l - 24)) + wave, lane, DEF, HALO, a.conv_w, a.norm_conv, MIX, SSC);
.LBB0_313:
	s_or_b64 exec, exec, s[0:1]
	s_cmpk_lt_u32 s98, 0xc0
	s_barrier
	s_cbranch_scc1 .LBB0_339
	s_mov_b64 s[0:1], exec
	v_readlane_b32 s2, v253, 23
	v_readlane_b32 s3, v253, 24
	s_and_b64 s[2:3], s[0:1], s[2:3]
	s_mov_b64 exec, s[2:3]
	s_cbranch_execz .LBB0_329
	v_mov_b32_e32 v0, 0x20448
	ds_read_b32 v1, v0
	s_waitcnt lgkmcnt(0)
	v_cmp_ne_u32_e32 vcc, 0, v1
	s_cbranch_vccnz .LBB0_329
	v_mov_b32_e32 v0, 0
	global_load_dword v1, v0, s[8:9] sc1
	s_waitcnt vmcnt(0)
	v_cmp_lt_u32_e32 vcc, 31, v1
	s_cbranch_vccnz .LBB0_328
	s_add_u32 s2, s96, 0x180200
	s_addc_u32 s3, s97, 0
	s_mov_b32 s12, 1
	s_branch .LBB0_318
